# v19: GLA pass A loop unrolled by two with double-buffered load registers: next-next chunk's tile loads are in flight during the current chunk (2-deep prefetch), counted waits per variant
# speedup vs baseline: 1.0062x; 1.0062x over previous
; #define LAS __attribute__((address_space(3)))
; __device__ __forceinline__ int opaque_tid() { int t = threadIdx.x; asm volatile("" : "+v"(t)); return t; }
; template <bool FULL>
; __device__ __forceinline__ void gla_pass(const Params& P, LAS unsigned char* lds, f32x4 (&S)[8][2], int bh, int c0, int L, bool dry) {
;     ...
;     const int tid = opaque_tid(), lane = tid & 63, w = tid >> 6, fr = lane & 15, g = lane >> 4;
;     bf16_t* PJ = (bf16_t*)(P.ws + WS_PJ); const float* DEC = (const float*)(P.ws + WS_DEC); const bf16_t* PB = (const bf16_t*)(P.ws + WS_PB);
;     LAS unsigned char* Lks = lds + O_KS; LAS unsigned char* Lqd = lds + O_QD; LAS unsigned char* Lv = lds + O_V; LAS unsigned char* Lp = lds + O_P; LAS unsigned char* Lst = lds + O_ST;
;     LAS float* red = (LAS float*)(lds + O_RED); LAS float* Ldec = (LAS float*)(lds + O_DEC);
;     const int b = bh >> 2, h = bh & 3;
;     u32x4 rk[2], rq[2], rv[4], rp; f32x4 rd = (f32x4){0.f, 0.f, 0.f, 0.f};
;     const unsigned gk = (unsigned)(tid * 16), gv = (unsigned)(tid * 16);
;     const unsigned lk = (unsigned)((tid >> 4) * KS_P + 16 * (tid & 15)), lq = (unsigned)((tid >> 4) * QD_P + 16 * (tid & 15)), lv = (unsigned)((tid >> 5) * V_P + 16 * (tid & 31)), lp = (unsigned)((tid >> 3) * P_P + 16 * (tid & 7));
;     ...
;     GLA_LOAD(c0); GLA_STORE();
;     __syncthreads();
;     for (int n = c0; n < c0 + L; ++n) {
;         const size_t row0 = (size_t)(b * SEQ + n * 64);
;         if (n + 1 < c0 + L) GLA_LOAD(n + 1);
.LBB0_656:
	s_or_b64 exec, exec, s[8:9]
	v_lshrrev_b32_e32 v5, 4, v10
	s_movk_i32 s8, 0x120
	v_lshrrev_b32_e32 v12, 5, v10
	v_mul_lo_u32 v5, v5, s8
	s_movk_i32 s8, 0x220
	v_and_b32_e32 v11, 0xf0, v0
	v_mul_lo_u32 v12, v12, s8
	v_add_u32_e32 v5, 0, v5
	v_and_b32_e32 v13, 0x1f0, v0
	v_add_u32_e32 v117, v5, v11
	v_add_u32_e32 v5, 0, v12
	v_mov_b32_e32 v9, v3
	v_mov_b32_e32 v7, v3
	v_add_u32_e32 v118, v5, v13
	v_add_u32_e32 v119, 0, v0
	s_waitcnt vmcnt(5)
	ds_write_b128 v117, v[20:23]
	s_waitcnt vmcnt(3)
	ds_write_b128 v117, v[28:31] offset:9216
	ds_write_b128 v118, v[32:35] offset:35840
	s_waitcnt vmcnt(2)
	ds_write_b128 v118, v[40:43] offset:44544
	s_waitcnt vmcnt(1)
	ds_write_b128 v118, v[44:47] offset:53248
	s_waitcnt vmcnt(0)
	ds_write_b128 v118, v[48:51] offset:61952
	s_and_saveexec_b64 s[8:9], s[4:5]
	v_add_u32_e32 v5, 0x25000, v119
	ds_write_b128 v5, v[52:55]
	s_or_b64 exec, exec, s[8:9]
	v_bfe_u32 v5, v10, 4, 2
	v_and_b32_e32 v11, 0xffffffc0, v10
	v_bfe_u32 v12, v10, 2, 2
	v_lshlrev_b32_e32 v10, 3, v10
	v_and_b32_e32 v10, 24, v10
	s_mov_b32 s9, 0
	s_add_i32 s8, s10, s11
	v_add_u32_e32 v13, 0, v10
	s_lshl_b64 s[10:11], s[8:9], 9
	v_add_u32_e32 v14, v13, v11
	v_lshl_add_u64 v[10:11], s[10:11], 0, v[0:1]
	s_mov_b64 s[12:13], 0xe008000
	s_lshl_b32 s22, s1, 6
	v_lshl_add_u64 v[100:101], v[10:11], 0, s[12:13]
	v_lshl_add_u64 v[10:11], s[10:11], 0, v[2:3]
	v_lshl_add_u64 v[8:9], s[10:11], 0, v[8:9]
	v_lshl_add_u64 v[6:7], s[10:11], 0, v[6:7]
	s_lshl_b64 s[10:11], s[8:9], 8
	v_lshl_add_u64 v[102:103], v[10:11], 0, s[12:13]
	v_lshl_add_u64 v[104:105], v[8:9], 0, s[12:13]
	v_lshl_add_u64 v[106:107], v[6:7], 0, s[12:13]
	v_lshl_add_u64 v[0:1], s[10:11], 0, v[0:1]
	s_mov_b64 s[12:13], 0xc004000
	s_add_i32 s8, s22, s0
	v_lshl_or_b32 v12, v5, 3, v12
	v_lshlrev_b32_e32 v120, 4, v5
	v_ashrrev_i32_e32 v5, 31, v4
	v_lshl_add_u64 v[108:109], v[0:1], 0, s[12:13]
	v_lshl_add_u64 v[0:1], s[10:11], 0, v[2:3]
	s_lshl_b64 s[8:9], s[8:9], 9
	v_lshl_add_u64 v[110:111], v[0:1], 0, s[12:13]
	v_lshl_add_u64 v[0:1], v[4:5], 2, s[8:9]
	s_mov_b64 s[8:9], 0x1a00200
	v_mul_u32_u24_e32 v15, 0x220, v12
	v_mul_u32_u24_e32 v12, 0x120, v12
	v_lshl_add_u64 v[112:113], v[0:1], 0, s[8:9]
	v_mov_b32_e32 v0, 0
	s_add_i32 s23, s0, 16
	s_mov_b32 s24, 1
	s_mov_b64 s[8:9], 0x8000
	s_mov_b64 s[10:11], 0x4000
	s_mov_b64 s[12:13], 0x200
	v_add_u32_e32 v116, v14, v15
	v_add_u32_e32 v115, v13, v12
	v_mov_b32_e32 v1, v0
	v_mov_b32_e32 v2, v0
	v_mov_b32_e32 v3, v0
	v_mov_b32_e32 v4, v0
	v_mov_b32_e32 v5, v0
	v_mov_b32_e32 v6, v0
	v_mov_b32_e32 v7, v0
	v_mov_b32_e32 v8, v0
	v_mov_b32_e32 v9, v0
	v_mov_b32_e32 v10, v0
	v_mov_b32_e32 v11, v0
	v_mov_b32_e32 v12, v0
	v_mov_b32_e32 v13, v0
	v_mov_b32_e32 v14, v0
	v_mov_b32_e32 v15, v0
	v_mov_b32_e32 v16, v0
	v_mov_b32_e32 v17, v0
	v_mov_b32_e32 v18, v0
	v_mov_b32_e32 v19, v0
	v_mov_b32_e32 v24, v0
	v_mov_b32_e32 v25, v0
	v_mov_b32_e32 v26, v0
	v_mov_b32_e32 v27, v0
	v_mov_b32_e32 v36, v0
	v_mov_b32_e32 v37, v0
	v_mov_b32_e32 v38, v0
	v_mov_b32_e32 v39, v0
	v_mov_b32_e32 v60, v0
	v_mov_b32_e32 v61, v0
	v_mov_b32_e32 v62, v0
	v_mov_b32_e32 v63, v0
	v_mov_b32_e32 v56, v0
	v_mov_b32_e32 v57, v0
	v_mov_b32_e32 v58, v0
	v_mov_b32_e32 v59, v0
	v_mov_b32_e32 v64, v0
	v_mov_b32_e32 v65, v0
	v_mov_b32_e32 v66, v0
	v_mov_b32_e32 v67, v0
	v_mov_b32_e32 v68, v0
	v_mov_b32_e32 v69, v0
	v_mov_b32_e32 v70, v0
	v_mov_b32_e32 v71, v0
	v_mov_b32_e32 v72, v0
	v_mov_b32_e32 v73, v0
	v_mov_b32_e32 v74, v0
	v_mov_b32_e32 v75, v0
	v_mov_b32_e32 v76, v0
	v_mov_b32_e32 v77, v0
	v_mov_b32_e32 v78, v0
	v_mov_b32_e32 v79, v0
	v_mov_b32_e32 v80, v0
	v_mov_b32_e32 v81, v0
	v_mov_b32_e32 v82, v0
	v_mov_b32_e32 v83, v0
	v_mov_b32_e32 v84, v0
	v_mov_b32_e32 v85, v0
	v_mov_b32_e32 v86, v0
	v_mov_b32_e32 v87, v0
	v_mov_b32_e32 v88, v0
	v_mov_b32_e32 v89, v0
	v_mov_b32_e32 v90, v0
	v_mov_b32_e32 v91, v0
	v_lshl_add_u64 v[178:179], s[70:71], 0, v[108:109]
	v_lshl_add_u64 v[180:181], s[70:71], 0, v[110:111]
	v_lshl_add_u64 v[182:183], s[70:71], 0, v[100:101]
	v_lshl_add_u64 v[184:185], s[70:71], 0, v[102:103]
	v_lshl_add_u64 v[186:187], s[70:71], 0, v[104:105]
	v_lshl_add_u64 v[188:189], s[70:71], 0, v[106:107]
	global_load_dwordx4 v[20:23], v[178:179], off
	global_load_dwordx4 v[28:31], v[180:181], off
	global_load_dwordx4 v[32:35], v[182:183], off
	global_load_dwordx4 v[40:43], v[184:185], off
	global_load_dwordx4 v[44:47], v[186:187], off
	global_load_dwordx4 v[48:51], v[188:189], off
	s_and_saveexec_b64 s[16:17], s[4:5]
	s_cbranch_execz .LpaP_nodec
	v_lshl_add_u64 v[190:191], s[70:71], 0, v[112:113]
	global_load_dwordx4 v[52:55], v[190:191], off
.LpaP_nodec:
	s_or_b64 exec, exec, s[16:17]
	v_lshl_add_u64 v[100:101], v[100:101], 0, s[8:9]
	v_lshl_add_u64 v[102:103], v[102:103], 0, s[8:9]
	v_lshl_add_u64 v[104:105], v[104:105], 0, s[8:9]
	v_lshl_add_u64 v[106:107], v[106:107], 0, s[8:9]
	v_lshl_add_u64 v[108:109], v[108:109], 0, s[10:11]
	v_lshl_add_u64 v[110:111], v[110:111], 0, s[10:11]
	v_lshl_add_u64 v[112:113], v[112:113], 0, s[12:13]
	s_waitcnt lgkmcnt(0)
	s_barrier
	s_branch .LpaE
.LpaE:
	s_cmp_lt_u32 s24, 15
	s_cbranch_scc0 .LpaE_noload
	v_lshl_add_u64 v[178:179], s[70:71], 0, v[108:109]
	v_lshl_add_u64 v[180:181], s[70:71], 0, v[110:111]
	v_lshl_add_u64 v[182:183], s[70:71], 0, v[100:101]
	v_lshl_add_u64 v[184:185], s[70:71], 0, v[102:103]
	v_lshl_add_u64 v[186:187], s[70:71], 0, v[104:105]
	v_lshl_add_u64 v[188:189], s[70:71], 0, v[106:107]
	global_load_dwordx4 v[150:153], v[178:179], off
	global_load_dwordx4 v[154:157], v[180:181], off
	global_load_dwordx4 v[158:161], v[182:183], off
	global_load_dwordx4 v[162:165], v[184:185], off
	global_load_dwordx4 v[166:169], v[186:187], off
	global_load_dwordx4 v[170:173], v[188:189], off
	s_and_saveexec_b64 s[16:17], s[4:5]
	s_cbranch_execz .LpaE_nodec
	v_lshl_add_u64 v[190:191], s[70:71], 0, v[112:113]
	global_load_dwordx4 v[174:177], v[190:191], off

; #define LAS __attribute__((address_space(3)))
; template <bool FULL>
; __device__ __forceinline__ void gla_pass(const Params& P, LAS unsigned char* lds, f32x4 (&S)[8][2], int bh, int c0, int L, bool dry) {
;     ...
; #pragma unroll
;         for (int kt = 0; kt < 8; ++kt) { const f32x4 dv = *(const LAS f32x4*)(Ldec + 16 * kt + 4 * g); S[kt][0] = S[kt][0] * dv; S[kt][1] = S[kt][1] * dv; }
; #pragma unroll
;         for (int k2 = 0; k2 < 2; ++k2)
; #pragma unroll
;             for (int kt = 0; kt < 8; ++kt) { const bf16x8 ak = trfrag(Lks, KS_P, 32 * k2, 32 * kt, g, fr);
;                 S[kt][0] = __builtin_amdgcn_mfma_f32_16x16x32_bf16(ak, vf[0][k2], S[kt][0], 0, 0, 0); S[kt][1] = __builtin_amdgcn_mfma_f32_16x16x32_bf16(ak, vf[1][k2], S[kt][1], 0, 0, 0); }
;     ...
;         __syncthreads();
;         if (FULL) gla_write_st(Lst, S, w, fr, g);
;         if (n + 1 < c0 + L) GLA_STORE();
.LpaE_noload:
	v_add_u32_e32 v121, 0, v120
	v_add_u32_e32 v146, 0x25000, v121
	ds_read_b128 v[122:125], v146
	ds_read_b64_tr_b16 v[98:99], v116 offset:38016
	ds_read_b64_tr_b16 v[96:97], v116 offset:35840
	ds_read_b64_tr_b16 v[94:95], v116 offset:38048
	ds_read_b64_tr_b16 v[92:93], v116 offset:35872
	ds_read_b128 v[126:129], v146 offset:64
	s_waitcnt lgkmcnt(5)
	v_pk_mul_f32 v[88:89], v[88:89], v[122:123]
	ds_read_b64_tr_b16 v[132:133], v115 offset:1152
	ds_read_b64_tr_b16 v[130:131], v115
	v_pk_mul_f32 v[90:91], v[90:91], v[124:125]
	v_pk_mul_f32 v[84:85], v[84:85], v[122:123]
	ds_read_b64_tr_b16 v[134:135], v115 offset:32
	ds_read_b64_tr_b16 v[138:139], v115 offset:64
	ds_read_b64_tr_b16 v[142:143], v115 offset:96
	ds_read_b64_tr_b16 v[136:137], v115 offset:1184
	ds_read_b64_tr_b16 v[140:141], v115 offset:1216
	ds_read_b64_tr_b16 v[144:145], v115 offset:1248
	v_pk_mul_f32 v[86:87], v[86:87], v[124:125]
	s_waitcnt lgkmcnt(8)
	v_pk_mul_f32 v[80:81], v[80:81], v[126:127]
	v_pk_mul_f32 v[82:83], v[82:83], v[128:129]
	ds_read_b128 v[122:125], v146 offset:128
	v_pk_mul_f32 v[76:77], v[76:77], v[126:127]
	v_pk_mul_f32 v[78:79], v[78:79], v[128:129]
	ds_read_b128 v[126:129], v146 offset:192
	s_waitcnt lgkmcnt(8)
	v_mfma_f32_16x16x32_bf16 v[88:91], v[130:133], v[96:99], v[88:91]
	s_waitcnt lgkmcnt(1)
	v_pk_mul_f32 v[72:73], v[72:73], v[122:123]
	v_pk_mul_f32 v[74:75], v[74:75], v[124:125]
	v_pk_mul_f32 v[68:69], v[68:69], v[122:123]
	v_pk_mul_f32 v[70:71], v[70:71], v[124:125]
	s_waitcnt lgkmcnt(0)
	v_pk_mul_f32 v[64:65], v[64:65], v[126:127]
	v_pk_mul_f32 v[66:67], v[66:67], v[128:129]
	ds_read_b128 v[122:125], v146 offset:256
	v_pk_mul_f32 v[56:57], v[56:57], v[126:127]
	v_pk_mul_f32 v[58:59], v[58:59], v[128:129]
	ds_read_b128 v[126:129], v146 offset:320
	v_mfma_f32_16x16x32_bf16 v[84:87], v[130:133], v[92:95], v[84:87]
	s_waitcnt lgkmcnt(1)
	v_pk_mul_f32 v[60:61], v[60:61], v[122:123]
	ds_read_b64_tr_b16 v[130:131], v115 offset:128
	ds_read_b64_tr_b16 v[132:133], v115 offset:1280
	v_pk_mul_f32 v[62:63], v[62:63], v[124:125]
	v_mfma_f32_16x16x32_bf16 v[80:83], v[134:137], v[96:99], v[80:83]
	v_mul_f32_e64 v36, v36, v122
	v_mul_f32_e64 v37, v37, v123
	v_pk_mul_f32 v[38:39], v[38:39], v[124:125]
	s_waitcnt lgkmcnt(2)
	v_pk_mul_f32 v[24:25], v[24:25], v[126:127]
	v_mfma_f32_16x16x32_bf16 v[76:79], v[134:137], v[92:95], v[76:79]
	v_mul_f32_e64 v26, v26, v128
	v_mul_f32_e64 v27, v27, v129
	v_pk_mul_f32 v[16:17], v[16:17], v[126:127]
	v_pk_mul_f32 v[18:19], v[18:19], v[128:129]
	v_mfma_f32_16x16x32_bf16 v[72:75], v[138:141], v[96:99], v[72:75]
	v_mfma_f32_16x16x32_bf16 v[68:71], v[138:141], v[92:95], v[68:71]
	v_mfma_f32_16x16x32_bf16 v[64:67], v[142:145], v[96:99], v[64:67]
	v_mfma_f32_16x16x32_bf16 v[56:59], v[142:145], v[92:95], v[56:59]
	ds_read_b64_tr_b16 v[134:135], v115 offset:160
	ds_read_b64_tr_b16 v[138:139], v115 offset:192
	ds_read_b64_tr_b16 v[142:143], v115 offset:224
	ds_read_b64_tr_b16 v[136:137], v115 offset:1312
	ds_read_b64_tr_b16 v[140:141], v115 offset:1344
	ds_read_b64_tr_b16 v[144:145], v115 offset:1376
	ds_read_b128 v[122:125], v146 offset:384
	ds_read_b128 v[126:129], v146 offset:448
	s_waitcnt lgkmcnt(8)
	v_mfma_f32_16x16x32_bf16 v[60:63], v[130:133], v[96:99], v[60:63]
	s_waitcnt lgkmcnt(1)
	v_pk_mul_f32 v[12:13], v[12:13], v[122:123]
	v_pk_mul_f32 v[14:15], v[14:15], v[124:125]
	v_pk_mul_f32 v[8:9], v[8:9], v[122:123]
	v_pk_mul_f32 v[10:11], v[10:11], v[124:125]
	s_waitcnt lgkmcnt(0)
	v_pk_mul_f32 v[4:5], v[4:5], v[126:127]
	v_pk_mul_f32 v[6:7], v[6:7], v[128:129]
	v_pk_mul_f32 v[0:1], v[0:1], v[126:127]
	v_pk_mul_f32 v[2:3], v[2:3], v[128:129]
	v_mfma_f32_16x16x32_bf16 v[36:39], v[130:133], v[92:95], v[36:39]
	v_mfma_f32_16x16x32_bf16 v[24:27], v[134:137], v[96:99], v[24:27]
	v_mfma_f32_16x16x32_bf16 v[16:19], v[134:137], v[92:95], v[16:19]
	ds_read_b64_tr_b16 v[130:131], v116 offset:53248
	ds_read_b64_tr_b16 v[132:133], v116 offset:55424
	ds_read_b64_tr_b16 v[136:137], v116 offset:55456
	ds_read_b64_tr_b16 v[134:135], v116 offset:53280
	v_mfma_f32_16x16x32_bf16 v[12:15], v[138:141], v[96:99], v[12:15]
	v_mfma_f32_16x16x32_bf16 v[8:11], v[138:141], v[92:95], v[8:11]
	v_mfma_f32_16x16x32_bf16 v[4:7], v[142:145], v[96:99], v[4:7]
	ds_read_b64_tr_b16 v[96:97], v115 offset:9216
	ds_read_b64_tr_b16 v[98:99], v115 offset:10368
	v_mfma_f32_16x16x32_bf16 v[0:3], v[142:145], v[92:95], v[0:3]
	ds_read_b64_tr_b16 v[92:93], v115 offset:9248
	ds_read_b64_tr_b16 v[122:123], v115 offset:9280
	ds_read_b64_tr_b16 v[126:127], v115 offset:9312
	ds_read_b64_tr_b16 v[94:95], v115 offset:10400
	ds_read_b64_tr_b16 v[124:125], v115 offset:10432
	ds_read_b64_tr_b16 v[128:129], v115 offset:10464
	s_waitcnt lgkmcnt(6)
	v_mfma_f32_16x16x32_bf16 v[88:91], v[96:99], v[130:133], v[88:91]
	v_mfma_f32_16x16x32_bf16 v[84:87], v[96:99], v[134:137], v[84:87]
	s_waitcnt lgkmcnt(2)
	v_mfma_f32_16x16x32_bf16 v[80:83], v[92:95], v[130:133], v[80:83]
	v_mfma_f32_16x16x32_bf16 v[76:79], v[92:95], v[134:137], v[76:79]
	ds_read_b64_tr_b16 v[92:93], v115 offset:9344
	ds_read_b64_tr_b16 v[94:95], v115 offset:10496
	s_waitcnt lgkmcnt(3)
	v_mfma_f32_16x16x32_bf16 v[72:75], v[122:125], v[130:133], v[72:75]
	v_mfma_f32_16x16x32_bf16 v[68:71], v[122:125], v[134:137], v[68:71]
	s_waitcnt lgkmcnt(2)
	v_mfma_f32_16x16x32_bf16 v[64:67], v[126:129], v[130:133], v[64:67]
	v_mfma_f32_16x16x32_bf16 v[56:59], v[126:129], v[134:137], v[56:59]
	ds_read_b64_tr_b16 v[96:97], v115 offset:9376
	ds_read_b64_tr_b16 v[122:123], v115 offset:9408
	ds_read_b64_tr_b16 v[126:127], v115 offset:9440
	ds_read_b64_tr_b16 v[98:99], v115 offset:10528
	ds_read_b64_tr_b16 v[124:125], v115 offset:10560
	ds_read_b64_tr_b16 v[128:129], v115 offset:10592
	s_waitcnt lgkmcnt(0)
	s_barrier
	v_mfma_f32_16x16x32_bf16 v[60:63], v[92:95], v[130:133], v[60:63]
	v_mfma_f32_16x16x32_bf16 v[36:39], v[92:95], v[134:137], v[36:39]
	v_mfma_f32_16x16x32_bf16 v[24:27], v[96:99], v[130:133], v[24:27]
	v_mfma_f32_16x16x32_bf16 v[16:19], v[96:99], v[134:137], v[16:19]
	v_mfma_f32_16x16x32_bf16 v[12:15], v[122:125], v[130:133], v[12:15]
	v_mfma_f32_16x16x32_bf16 v[8:11], v[122:125], v[134:137], v[8:11]
	v_mfma_f32_16x16x32_bf16 v[4:7], v[126:129], v[130:133], v[4:7]
	v_mfma_f32_16x16x32_bf16 v[0:3], v[126:129], v[134:137], v[0:3]
	s_cmp_lt_u32 s24, 15
	s_cbranch_scc0 .LpaE_w1
	s_waitcnt vmcnt(11)
	ds_write_b128 v117, v[20:23]
	s_waitcnt vmcnt(10)
	ds_write_b128 v117, v[28:31] offset:9216
	s_waitcnt vmcnt(9)
	ds_write_b128 v118, v[32:35] offset:35840
	s_waitcnt vmcnt(8)
	ds_write_b128 v118, v[40:43] offset:44544
	s_waitcnt vmcnt(7)
	ds_write_b128 v118, v[44:47] offset:53248
	s_waitcnt vmcnt(6)
	ds_write_b128 v118, v[48:51] offset:61952
	s_branch .LpaE_wd
; template <bool FULL>
; __device__ __forceinline__ void gla_pass(const Params& P, LAS unsigned char* lds, f32x4 (&S)[8][2], int bh, int c0, int L, bool dry) {
;     ...
;     GLA_LOAD(c0); GLA_STORE();
;     __syncthreads();
;     for (int n = c0; n < c0 + L; ++n) {
;         const size_t row0 = (size_t)(b * SEQ + n * 64);
;         if (n + 1 < c0 + L) GLA_LOAD(n + 1);
.LpaE_w1:
	s_waitcnt vmcnt(5)
	ds_write_b128 v117, v[20:23]
	s_waitcnt vmcnt(4)
	ds_write_b128 v117, v[28:31] offset:9216
	s_waitcnt vmcnt(3)
	ds_write_b128 v118, v[32:35] offset:35840
	s_waitcnt vmcnt(2)
	ds_write_b128 v118, v[40:43] offset:44544
	s_waitcnt vmcnt(1)
	ds_write_b128 v118, v[44:47] offset:53248
	s_waitcnt vmcnt(0)
	ds_write_b128 v118, v[48:51] offset:61952
.LpaE_wd:
	s_and_saveexec_b64 s[14:15], s[4:5]
	s_cbranch_execz .LpaE_nodw
	s_waitcnt vmcnt(7)
	v_add_u32_e32 v92, 0x25000, v119
	ds_write_b128 v92, v[52:55]
.LpaE_nodw:
	s_or_b64 exec, exec, s[14:15]
	s_add_i32 s24, s24, 1
	v_lshl_add_u64 v[100:101], v[100:101], 0, s[8:9]
	v_lshl_add_u64 v[102:103], v[102:103], 0, s[8:9]
	v_lshl_add_u64 v[104:105], v[104:105], 0, s[8:9]
	v_lshl_add_u64 v[106:107], v[106:107], 0, s[8:9]
	v_lshl_add_u64 v[108:109], v[108:109], 0, s[10:11]
	v_lshl_add_u64 v[110:111], v[110:111], 0, s[10:11]
	s_cmp_lg_u32 s24, 16
	v_lshl_add_u64 v[112:113], v[112:113], 0, s[12:13]
	s_waitcnt lgkmcnt(0)
	s_barrier
	s_cbranch_scc0 .LBB0_668
.LpaO:
	s_cmp_lt_u32 s24, 15
	s_cbranch_scc0 .LpaO_noload
	v_lshl_add_u64 v[178:179], s[70:71], 0, v[108:109]
	v_lshl_add_u64 v[180:181], s[70:71], 0, v[110:111]
	v_lshl_add_u64 v[182:183], s[70:71], 0, v[100:101]
	v_lshl_add_u64 v[184:185], s[70:71], 0, v[102:103]
	v_lshl_add_u64 v[186:187], s[70:71], 0, v[104:105]
	v_lshl_add_u64 v[188:189], s[70:71], 0, v[106:107]
	global_load_dwordx4 v[20:23], v[178:179], off
	global_load_dwordx4 v[28:31], v[180:181], off
	global_load_dwordx4 v[32:35], v[182:183], off
	global_load_dwordx4 v[40:43], v[184:185], off
	global_load_dwordx4 v[44:47], v[186:187], off
	global_load_dwordx4 v[48:51], v[188:189], off
	s_and_saveexec_b64 s[16:17], s[4:5]
	s_cbranch_execz .LpaO_nodec
	v_lshl_add_u64 v[190:191], s[70:71], 0, v[112:113]
	global_load_dwordx4 v[52:55], v[190:191], off

; #define LAS __attribute__((address_space(3)))
; template <bool FULL>
; __device__ __forceinline__ void gla_pass(const Params& P, LAS unsigned char* lds, f32x4 (&S)[8][2], int bh, int c0, int L, bool dry) {
;     ...
; #pragma unroll
;         for (int kt = 0; kt < 8; ++kt) { const f32x4 dv = *(const LAS f32x4*)(Ldec + 16 * kt + 4 * g); S[kt][0] = S[kt][0] * dv; S[kt][1] = S[kt][1] * dv; }
; #pragma unroll
;         for (int k2 = 0; k2 < 2; ++k2)
; #pragma unroll
;             for (int kt = 0; kt < 8; ++kt) { const bf16x8 ak = trfrag(Lks, KS_P, 32 * k2, 32 * kt, g, fr);
;                 S[kt][0] = __builtin_amdgcn_mfma_f32_16x16x32_bf16(ak, vf[0][k2], S[kt][0], 0, 0, 0); S[kt][1] = __builtin_amdgcn_mfma_f32_16x16x32_bf16(ak, vf[1][k2], S[kt][1], 0, 0, 0); }
;     ...
;         __syncthreads();
;         if (FULL) gla_write_st(Lst, S, w, fr, g);
;         if (n + 1 < c0 + L) GLA_STORE();
.LpaO_noload:
	v_add_u32_e32 v121, 0, v120
	v_add_u32_e32 v146, 0x25000, v121
	ds_read_b128 v[122:125], v146
	ds_read_b64_tr_b16 v[98:99], v116 offset:38016
	ds_read_b64_tr_b16 v[96:97], v116 offset:35840
	ds_read_b64_tr_b16 v[94:95], v116 offset:38048
	ds_read_b64_tr_b16 v[92:93], v116 offset:35872
	ds_read_b128 v[126:129], v146 offset:64
	s_waitcnt lgkmcnt(5)
	v_pk_mul_f32 v[88:89], v[88:89], v[122:123]
	ds_read_b64_tr_b16 v[132:133], v115 offset:1152
	ds_read_b64_tr_b16 v[130:131], v115
	v_pk_mul_f32 v[90:91], v[90:91], v[124:125]
	v_pk_mul_f32 v[84:85], v[84:85], v[122:123]
	ds_read_b64_tr_b16 v[134:135], v115 offset:32
	ds_read_b64_tr_b16 v[138:139], v115 offset:64
	ds_read_b64_tr_b16 v[142:143], v115 offset:96
	ds_read_b64_tr_b16 v[136:137], v115 offset:1184
	ds_read_b64_tr_b16 v[140:141], v115 offset:1216
	ds_read_b64_tr_b16 v[144:145], v115 offset:1248
	v_pk_mul_f32 v[86:87], v[86:87], v[124:125]
	s_waitcnt lgkmcnt(8)
	v_pk_mul_f32 v[80:81], v[80:81], v[126:127]
	v_pk_mul_f32 v[82:83], v[82:83], v[128:129]
	ds_read_b128 v[122:125], v146 offset:128
	v_pk_mul_f32 v[76:77], v[76:77], v[126:127]
	v_pk_mul_f32 v[78:79], v[78:79], v[128:129]
	ds_read_b128 v[126:129], v146 offset:192
	s_waitcnt lgkmcnt(8)
	v_mfma_f32_16x16x32_bf16 v[88:91], v[130:133], v[96:99], v[88:91]
	s_waitcnt lgkmcnt(1)
	v_pk_mul_f32 v[72:73], v[72:73], v[122:123]
	v_pk_mul_f32 v[74:75], v[74:75], v[124:125]
	v_pk_mul_f32 v[68:69], v[68:69], v[122:123]
	v_pk_mul_f32 v[70:71], v[70:71], v[124:125]
	s_waitcnt lgkmcnt(0)
	v_pk_mul_f32 v[64:65], v[64:65], v[126:127]
	v_pk_mul_f32 v[66:67], v[66:67], v[128:129]
	ds_read_b128 v[122:125], v146 offset:256
	v_pk_mul_f32 v[56:57], v[56:57], v[126:127]
	v_pk_mul_f32 v[58:59], v[58:59], v[128:129]
	ds_read_b128 v[126:129], v146 offset:320
	v_mfma_f32_16x16x32_bf16 v[84:87], v[130:133], v[92:95], v[84:87]
	s_waitcnt lgkmcnt(1)
	v_pk_mul_f32 v[60:61], v[60:61], v[122:123]
	ds_read_b64_tr_b16 v[130:131], v115 offset:128
	ds_read_b64_tr_b16 v[132:133], v115 offset:1280
	v_pk_mul_f32 v[62:63], v[62:63], v[124:125]
	v_mfma_f32_16x16x32_bf16 v[80:83], v[134:137], v[96:99], v[80:83]
	v_mul_f32_e64 v36, v36, v122
	v_mul_f32_e64 v37, v37, v123
	v_pk_mul_f32 v[38:39], v[38:39], v[124:125]
	s_waitcnt lgkmcnt(2)
	v_pk_mul_f32 v[24:25], v[24:25], v[126:127]
	v_mfma_f32_16x16x32_bf16 v[76:79], v[134:137], v[92:95], v[76:79]
	v_mul_f32_e64 v26, v26, v128
	v_mul_f32_e64 v27, v27, v129
	v_pk_mul_f32 v[16:17], v[16:17], v[126:127]
	v_pk_mul_f32 v[18:19], v[18:19], v[128:129]
	v_mfma_f32_16x16x32_bf16 v[72:75], v[138:141], v[96:99], v[72:75]
	v_mfma_f32_16x16x32_bf16 v[68:71], v[138:141], v[92:95], v[68:71]
	v_mfma_f32_16x16x32_bf16 v[64:67], v[142:145], v[96:99], v[64:67]
	v_mfma_f32_16x16x32_bf16 v[56:59], v[142:145], v[92:95], v[56:59]
	ds_read_b64_tr_b16 v[134:135], v115 offset:160
	ds_read_b64_tr_b16 v[138:139], v115 offset:192
	ds_read_b64_tr_b16 v[142:143], v115 offset:224
	ds_read_b64_tr_b16 v[136:137], v115 offset:1312
	ds_read_b64_tr_b16 v[140:141], v115 offset:1344
	ds_read_b64_tr_b16 v[144:145], v115 offset:1376
	ds_read_b128 v[122:125], v146 offset:384
	ds_read_b128 v[126:129], v146 offset:448
	s_waitcnt lgkmcnt(8)
	v_mfma_f32_16x16x32_bf16 v[60:63], v[130:133], v[96:99], v[60:63]
	s_waitcnt lgkmcnt(1)
	v_pk_mul_f32 v[12:13], v[12:13], v[122:123]
	v_pk_mul_f32 v[14:15], v[14:15], v[124:125]
	v_pk_mul_f32 v[8:9], v[8:9], v[122:123]
	v_pk_mul_f32 v[10:11], v[10:11], v[124:125]
	s_waitcnt lgkmcnt(0)
	v_pk_mul_f32 v[4:5], v[4:5], v[126:127]
	v_pk_mul_f32 v[6:7], v[6:7], v[128:129]
	v_pk_mul_f32 v[0:1], v[0:1], v[126:127]
	v_pk_mul_f32 v[2:3], v[2:3], v[128:129]
	v_mfma_f32_16x16x32_bf16 v[36:39], v[130:133], v[92:95], v[36:39]
	v_mfma_f32_16x16x32_bf16 v[24:27], v[134:137], v[96:99], v[24:27]
	v_mfma_f32_16x16x32_bf16 v[16:19], v[134:137], v[92:95], v[16:19]
	ds_read_b64_tr_b16 v[130:131], v116 offset:53248
	ds_read_b64_tr_b16 v[132:133], v116 offset:55424
	ds_read_b64_tr_b16 v[136:137], v116 offset:55456
	ds_read_b64_tr_b16 v[134:135], v116 offset:53280
	v_mfma_f32_16x16x32_bf16 v[12:15], v[138:141], v[96:99], v[12:15]
	v_mfma_f32_16x16x32_bf16 v[8:11], v[138:141], v[92:95], v[8:11]
	v_mfma_f32_16x16x32_bf16 v[4:7], v[142:145], v[96:99], v[4:7]
	ds_read_b64_tr_b16 v[96:97], v115 offset:9216
	ds_read_b64_tr_b16 v[98:99], v115 offset:10368
	v_mfma_f32_16x16x32_bf16 v[0:3], v[142:145], v[92:95], v[0:3]
	ds_read_b64_tr_b16 v[92:93], v115 offset:9248
	ds_read_b64_tr_b16 v[122:123], v115 offset:9280
	ds_read_b64_tr_b16 v[126:127], v115 offset:9312
	ds_read_b64_tr_b16 v[94:95], v115 offset:10400
	ds_read_b64_tr_b16 v[124:125], v115 offset:10432
	ds_read_b64_tr_b16 v[128:129], v115 offset:10464
	s_waitcnt lgkmcnt(6)
	v_mfma_f32_16x16x32_bf16 v[88:91], v[96:99], v[130:133], v[88:91]
	v_mfma_f32_16x16x32_bf16 v[84:87], v[96:99], v[134:137], v[84:87]
	s_waitcnt lgkmcnt(2)
	v_mfma_f32_16x16x32_bf16 v[80:83], v[92:95], v[130:133], v[80:83]
	v_mfma_f32_16x16x32_bf16 v[76:79], v[92:95], v[134:137], v[76:79]
	ds_read_b64_tr_b16 v[92:93], v115 offset:9344
	ds_read_b64_tr_b16 v[94:95], v115 offset:10496
	s_waitcnt lgkmcnt(3)
	v_mfma_f32_16x16x32_bf16 v[72:75], v[122:125], v[130:133], v[72:75]
	v_mfma_f32_16x16x32_bf16 v[68:71], v[122:125], v[134:137], v[68:71]
	s_waitcnt lgkmcnt(2)
	v_mfma_f32_16x16x32_bf16 v[64:67], v[126:129], v[130:133], v[64:67]
	v_mfma_f32_16x16x32_bf16 v[56:59], v[126:129], v[134:137], v[56:59]
	ds_read_b64_tr_b16 v[96:97], v115 offset:9376
	ds_read_b64_tr_b16 v[122:123], v115 offset:9408
	ds_read_b64_tr_b16 v[126:127], v115 offset:9440
	ds_read_b64_tr_b16 v[98:99], v115 offset:10528
	ds_read_b64_tr_b16 v[124:125], v115 offset:10560
	ds_read_b64_tr_b16 v[128:129], v115 offset:10592
	s_waitcnt lgkmcnt(0)
	s_barrier
	v_mfma_f32_16x16x32_bf16 v[60:63], v[92:95], v[130:133], v[60:63]
	v_mfma_f32_16x16x32_bf16 v[36:39], v[92:95], v[134:137], v[36:39]
	v_mfma_f32_16x16x32_bf16 v[24:27], v[96:99], v[130:133], v[24:27]
	v_mfma_f32_16x16x32_bf16 v[16:19], v[96:99], v[134:137], v[16:19]
	v_mfma_f32_16x16x32_bf16 v[12:15], v[122:125], v[130:133], v[12:15]
	v_mfma_f32_16x16x32_bf16 v[8:11], v[122:125], v[134:137], v[8:11]
	v_mfma_f32_16x16x32_bf16 v[4:7], v[126:129], v[130:133], v[4:7]
	v_mfma_f32_16x16x32_bf16 v[0:3], v[126:129], v[134:137], v[0:3]
	s_cmp_lt_u32 s24, 15
	s_cbranch_scc0 .LpaO_w1
	s_waitcnt vmcnt(11)
	ds_write_b128 v117, v[150:153]
	s_waitcnt vmcnt(10)
	ds_write_b128 v117, v[154:157] offset:9216
	s_waitcnt vmcnt(9)
	ds_write_b128 v118, v[158:161] offset:35840
	s_waitcnt vmcnt(8)
	ds_write_b128 v118, v[162:165] offset:44544
	s_waitcnt vmcnt(7)
	ds_write_b128 v118, v[166:169] offset:53248
	s_waitcnt vmcnt(6)
	ds_write_b128 v118, v[170:173] offset:61952
	s_branch .LpaO_wd
; #define LAS __attribute__((address_space(3)))
; __device__ __forceinline__ float bflo(unsigned w) { return __uint_as_float(w << 16); }
; __device__ __forceinline__ float bfhi(unsigned w) { return __uint_as_float(w & 0xffff0000u); }
; __device__ __forceinline__ unsigned pk2(float lo, float hi) { return f2bf(lo) | (f2bf(hi) << 16); }
; template <bool FULL>
; __device__ __forceinline__ void gla_pass(const Params& P, LAS unsigned char* lds, f32x4 (&S)[8][2], int bh, int c0, int L, bool dry) {
;     ...
;         __syncthreads();
;         if (FULL) gla_write_st(Lst, S, w, fr, g);
;         if (n + 1 < c0 + L) GLA_STORE();
;         if (FULL) {
;             f32x4 gn[2];
; #pragma unroll
;             for (int vt = 0; vt < 2; ++vt) gn[vt] = *(const f32x4*)(P.gla_norm_g + 32 * w + 4 * g + 16 * vt);
; #pragma unroll
;             for (int tt = 0; tt < 4; ++tt) {
;                 const int t = 16 * tt + fr;
;                 const f32x4 r0 = *(const LAS f32x4*)(red + t * 8), r1 = *(const LAS f32x4*)(red + t * 8 + 4);
;                 const float rstd = 1.0f / sqrtf(((r0[0] + r0[1]) + (r0[2] + r0[3]) + (r1[0] + r1[1]) + (r1[2] + r1[3])) * (1.0f / 256.0f) + RMS_EPS);
; #pragma unroll
;                 for (int vt = 0; vt < 2; ++vt) {
;                     bf16_t* op = (bf16_t*)P.out + (row0 + t) * 2048 + 1024 + h * 256 + 32 * w + 16 * vt + 4 * g;
;                     const u32x2 z = zb[vt][tt]; const f32x4 ov = o[vt][tt] * rstd * gn[vt];
;                     u32x2 r; r.x = pk2(ov[0] * bflo(z.x), ov[1] * bfhi(z.x)); r.y = pk2(ov[2] * bflo(z.y), ov[3] * bfhi(z.y));
;                     if (!dry) *(u32x2*)op = r;
;                 }
;             }
;         }
;         __syncthreads();
;     }
.LpaO_w1:
	s_waitcnt vmcnt(5)
	ds_write_b128 v117, v[150:153]
	s_waitcnt vmcnt(4)
	ds_write_b128 v117, v[154:157] offset:9216
	s_waitcnt vmcnt(3)
	ds_write_b128 v118, v[158:161] offset:35840
	s_waitcnt vmcnt(2)
	ds_write_b128 v118, v[162:165] offset:44544
	s_waitcnt vmcnt(1)
	ds_write_b128 v118, v[166:169] offset:53248
	s_waitcnt vmcnt(0)
	ds_write_b128 v118, v[170:173] offset:61952
.LpaO_wd:
	s_and_saveexec_b64 s[14:15], s[4:5]
	s_cbranch_execz .LpaO_nodw
	s_waitcnt vmcnt(7)
	v_add_u32_e32 v92, 0x25000, v119
	ds_write_b128 v92, v[174:177]
.LpaO_nodw:
	s_or_b64 exec, exec, s[14:15]
	s_add_i32 s24, s24, 1
	v_lshl_add_u64 v[100:101], v[100:101], 0, s[8:9]
	v_lshl_add_u64 v[102:103], v[102:103], 0, s[8:9]
	v_lshl_add_u64 v[104:105], v[104:105], 0, s[8:9]
	v_lshl_add_u64 v[106:107], v[106:107], 0, s[8:9]
	v_lshl_add_u64 v[108:109], v[108:109], 0, s[10:11]
	v_lshl_add_u64 v[110:111], v[110:111], 0, s[10:11]
	s_cmp_lg_u32 s24, 16
	v_lshl_add_u64 v[112:113], v[112:113], 0, s[12:13]
	s_waitcnt lgkmcnt(0)
	s_barrier
	s_cbranch_scc0 .LBB0_668
	s_branch .LpaE
